# g1 K-loop regrouped into double phases (32 MFMA per barrier interval, half the barriers, same DMA order); plus hand-pipelined norm0 and epilogue-interval alignment
# speedup vs baseline: 1.0077x; 1.0077x over previous
.Lg1_enter:
.LBB0_391:
	s_add_u32 s14, s30, 0xfffc0080
	s_addc_u32 s15, s31, -1
	s_add_i32 s20, 16, 0x10000
	v_add_u32_e32 v130, s20, v156
	ds_read_b128 v[166:169], v130
	ds_read_b128 v[170:173], v130 offset:1024
	ds_read_b128 v[174:177], v130 offset:2048
	ds_read_b128 v[178:181], v130 offset:3072
	s_cmp_eq_u32 s92, 12
	s_cselect_b32 s19, s1, s15
	s_cselect_b32 s18, s13, s14
	s_cselect_b32 s15, s9, s47
	s_cselect_b32 s14, s24, s25
	v_lshl_add_u64 v[130:131], s[30:31], 0, v[150:151]
	s_add_i32 m0, s34, 0xc000
	ds_read_b128 v[182:185], v158
	ds_read_b128 v[186:189], v158 offset:1024
	ds_read_b128 v[190:193], v158 offset:2048
	ds_read_b128 v[194:197], v158 offset:3072
	ds_read_b128 v[198:201], v158 offset:4096
	ds_read_b128 v[202:205], v158 offset:5120
	ds_read_b128 v[206:209], v158 offset:6144
	ds_read_b128 v[210:213], v158 offset:7168
	global_load_lds_dwordx4 v[130:131], off
	v_lshl_add_u64 v[130:131], s[30:31], 0, v[152:153]
	s_add_i32 m0, s34, 0xe000
	s_add_i32 s50, 16, 0x14000
	global_load_lds_dwordx4 v[130:131], off
	v_add_u32_e32 v130, s50, v156
	s_add_i32 s20, s20, s5
	ds_read_b128 v[214:217], v130
	ds_read_b128 v[218:221], v130 offset:1024
	ds_read_b128 v[222:225], v130 offset:2048
	ds_read_b128 v[226:229], v130 offset:3072
	s_waitcnt vmcnt(8) lgkmcnt(0)
	s_barrier
	s_setprio 1
	v_mfma_f32_16x16x32_bf16 v[116:119], v[166:169], v[182:185], v[116:119]
	v_mfma_f32_16x16x32_bf16 v[112:115], v[174:177], v[182:185], v[112:115]
	v_mfma_f32_16x16x32_bf16 v[100:103], v[166:169], v[190:193], v[100:103]
	v_mfma_f32_16x16x32_bf16 v[96:99], v[174:177], v[190:193], v[96:99]
	v_mfma_f32_16x16x32_bf16 v[84:87], v[166:169], v[198:201], v[84:87]
	v_mfma_f32_16x16x32_bf16 v[80:83], v[174:177], v[198:201], v[80:83]
	v_mfma_f32_16x16x32_bf16 v[68:71], v[166:169], v[206:209], v[68:71]
	v_mfma_f32_16x16x32_bf16 v[64:67], v[174:177], v[206:209], v[64:67]
	v_mfma_f32_16x16x32_bf16 v[116:119], v[170:173], v[186:189], v[116:119]
	v_mfma_f32_16x16x32_bf16 v[112:115], v[178:181], v[186:189], v[112:115]
	v_mfma_f32_16x16x32_bf16 v[100:103], v[170:173], v[194:197], v[100:103]
	v_mfma_f32_16x16x32_bf16 v[96:99], v[178:181], v[194:197], v[96:99]
	v_mfma_f32_16x16x32_bf16 v[84:87], v[170:173], v[202:205], v[84:87]
	v_mfma_f32_16x16x32_bf16 v[80:83], v[178:181], v[202:205], v[80:83]
	v_mfma_f32_16x16x32_bf16 v[68:71], v[170:173], v[210:213], v[68:71]
	v_mfma_f32_16x16x32_bf16 v[64:67], v[178:181], v[210:213], v[64:67]
	v_mfma_f32_16x16x32_bf16 v[124:127], v[214:217], v[182:185], v[124:127]
	v_mfma_f32_16x16x32_bf16 v[120:123], v[222:225], v[182:185], v[120:123]
	v_mfma_f32_16x16x32_bf16 v[108:111], v[214:217], v[190:193], v[108:111]
	v_mfma_f32_16x16x32_bf16 v[104:107], v[222:225], v[190:193], v[104:107]
	v_mfma_f32_16x16x32_bf16 v[92:95], v[214:217], v[198:201], v[92:95]
	v_mfma_f32_16x16x32_bf16 v[88:91], v[222:225], v[198:201], v[88:91]
	v_mfma_f32_16x16x32_bf16 v[76:79], v[214:217], v[206:209], v[76:79]
	v_mfma_f32_16x16x32_bf16 v[72:75], v[222:225], v[206:209], v[72:75]
	v_mfma_f32_16x16x32_bf16 v[124:127], v[218:221], v[186:189], v[124:127]
	v_mfma_f32_16x16x32_bf16 v[120:123], v[226:229], v[186:189], v[120:123]
	v_mfma_f32_16x16x32_bf16 v[108:111], v[218:221], v[194:197], v[108:111]
	v_mfma_f32_16x16x32_bf16 v[104:107], v[226:229], v[194:197], v[104:107]
	v_mfma_f32_16x16x32_bf16 v[92:95], v[218:221], v[202:205], v[92:95]
	v_mfma_f32_16x16x32_bf16 v[88:91], v[226:229], v[202:205], v[88:91]
	v_mfma_f32_16x16x32_bf16 v[76:79], v[218:221], v[210:213], v[76:79]
	v_mfma_f32_16x16x32_bf16 v[72:75], v[226:229], v[210:213], v[72:75]
	s_setprio 0
	s_barrier
	ds_read_b128 v[182:185], v158 offset:16384
	ds_read_b128 v[186:189], v158 offset:17408
	ds_read_b128 v[190:193], v158 offset:18432
	ds_read_b128 v[194:197], v158 offset:19456
	ds_read_b128 v[198:201], v158 offset:20480
	ds_read_b128 v[202:205], v158 offset:21504
	ds_read_b128 v[206:209], v158 offset:22528
	ds_read_b128 v[210:213], v158 offset:23552
	v_lshl_add_u64 v[130:131], s[14:15], 0, v[128:129]
	s_mov_b32 m0, s20
	v_lshl_add_u64 v[132:133], s[14:15], 0, v[144:145]
	global_load_lds_dwordx4 v[130:131], off
	s_add_i32 m0, s20, 0x2000
	v_lshl_add_u64 v[134:135], s[18:19], 0, v[148:149]
	global_load_lds_dwordx4 v[132:133], off
	s_mov_b32 m0, s34
	v_lshl_add_u64 v[136:137], s[18:19], 0, v[146:147]
	global_load_lds_dwordx4 v[134:135], off
	s_mov_b32 m0, s35
	s_add_u32 s48, s14, 0x40000
	s_addc_u32 s49, s15, 0
	global_load_lds_dwordx4 v[136:137], off
	s_add_i32 s20, s50, s5
	v_lshl_add_u64 v[138:139], s[48:49], 0, v[128:129]
	s_mov_b32 m0, s20
	s_nop 0
	global_load_lds_dwordx4 v[138:139], off
	v_lshl_add_u64 v[138:139], s[48:49], 0, v[144:145]
	s_add_i32 m0, s20, 0x2000
	s_nop 0
	global_load_lds_dwordx4 v[138:139], off
	s_waitcnt vmcnt(8) lgkmcnt(0)
	s_barrier
	s_setprio 1
	v_mfma_f32_16x16x32_bf16 v[52:55], v[166:169], v[182:185], v[52:55]
	v_mfma_f32_16x16x32_bf16 v[48:51], v[174:177], v[182:185], v[48:51]
	v_mfma_f32_16x16x32_bf16 v[36:39], v[166:169], v[190:193], v[36:39]
	v_mfma_f32_16x16x32_bf16 v[32:35], v[174:177], v[190:193], v[32:35]
	v_mfma_f32_16x16x32_bf16 v[20:23], v[166:169], v[198:201], v[20:23]
	v_mfma_f32_16x16x32_bf16 v[16:19], v[174:177], v[198:201], v[16:19]
	v_mfma_f32_16x16x32_bf16 v[4:7], v[166:169], v[206:209], v[4:7]
	v_mfma_f32_16x16x32_bf16 v[0:3], v[174:177], v[206:209], v[0:3]
	v_mfma_f32_16x16x32_bf16 v[52:55], v[170:173], v[186:189], v[52:55]
	v_mfma_f32_16x16x32_bf16 v[48:51], v[178:181], v[186:189], v[48:51]
	v_mfma_f32_16x16x32_bf16 v[36:39], v[170:173], v[194:197], v[36:39]
	v_mfma_f32_16x16x32_bf16 v[32:35], v[178:181], v[194:197], v[32:35]
	v_mfma_f32_16x16x32_bf16 v[20:23], v[170:173], v[202:205], v[20:23]
	v_mfma_f32_16x16x32_bf16 v[16:19], v[178:181], v[202:205], v[16:19]
	v_mfma_f32_16x16x32_bf16 v[4:7], v[170:173], v[210:213], v[4:7]
	v_mfma_f32_16x16x32_bf16 v[0:3], v[178:181], v[210:213], v[0:3]
	v_mfma_f32_16x16x32_bf16 v[60:63], v[214:217], v[182:185], v[60:63]
	v_mfma_f32_16x16x32_bf16 v[56:59], v[222:225], v[182:185], v[56:59]
	v_mfma_f32_16x16x32_bf16 v[44:47], v[214:217], v[190:193], v[44:47]
	v_mfma_f32_16x16x32_bf16 v[40:43], v[222:225], v[190:193], v[40:43]
	v_mfma_f32_16x16x32_bf16 v[28:31], v[214:217], v[198:201], v[28:31]
	v_mfma_f32_16x16x32_bf16 v[24:27], v[222:225], v[198:201], v[24:27]
	v_mfma_f32_16x16x32_bf16 v[12:15], v[214:217], v[206:209], v[12:15]
	v_mfma_f32_16x16x32_bf16 v[8:11], v[222:225], v[206:209], v[8:11]
	v_mfma_f32_16x16x32_bf16 v[60:63], v[218:221], v[186:189], v[60:63]
	v_mfma_f32_16x16x32_bf16 v[56:59], v[226:229], v[186:189], v[56:59]
	v_mfma_f32_16x16x32_bf16 v[44:47], v[218:221], v[194:197], v[44:47]
	v_mfma_f32_16x16x32_bf16 v[40:43], v[226:229], v[194:197], v[40:43]
	v_mfma_f32_16x16x32_bf16 v[28:31], v[218:221], v[202:205], v[28:31]
	v_mfma_f32_16x16x32_bf16 v[24:27], v[226:229], v[202:205], v[24:27]
	v_mfma_f32_16x16x32_bf16 v[12:15], v[218:221], v[210:213], v[12:15]
	v_mfma_f32_16x16x32_bf16 v[8:11], v[226:229], v[210:213], v[8:11]
	s_setprio 0
	s_add_i32 s20, 16, 0x18000
	v_add_u32_e32 v138, s20, v156
	s_barrier
	ds_read_b128 v[166:169], v138
	ds_read_b128 v[170:173], v138 offset:1024
	ds_read_b128 v[174:177], v138 offset:2048
	ds_read_b128 v[178:181], v138 offset:3072
	s_add_u32 s18, s18, 0x40000
	s_addc_u32 s19, s19, 0
	s_mov_b32 m0, s36
	v_lshl_add_u64 v[214:215], s[18:19], 0, v[148:149]
	ds_read_b128 v[182:185], v158 offset:32768
	ds_read_b128 v[186:189], v158 offset:33792
	ds_read_b128 v[190:193], v158 offset:34816
	ds_read_b128 v[194:197], v158 offset:35840
	ds_read_b128 v[198:201], v158 offset:36864
	ds_read_b128 v[202:205], v158 offset:37888
	ds_read_b128 v[206:209], v158 offset:38912
	ds_read_b128 v[210:213], v158 offset:39936
	global_load_lds_dwordx4 v[214:215], off
	v_lshl_add_u64 v[214:215], s[18:19], 0, v[146:147]
	s_mov_b32 m0, s37
	s_add_i32 s18, 16, 0x1c000
	global_load_lds_dwordx4 v[214:215], off
	s_add_i32 s19, s20, s5
	v_add_u32_e32 v138, s18, v156
	ds_read_b128 v[214:217], v138
	ds_read_b128 v[218:221], v138 offset:1024
	ds_read_b128 v[222:225], v138 offset:2048
	ds_read_b128 v[226:229], v138 offset:3072
	s_waitcnt vmcnt(8) lgkmcnt(0)
	s_barrier
	s_setprio 1
	v_mfma_f32_16x16x32_bf16 v[116:119], v[166:169], v[182:185], v[116:119]
	v_mfma_f32_16x16x32_bf16 v[112:115], v[174:177], v[182:185], v[112:115]
	v_mfma_f32_16x16x32_bf16 v[100:103], v[166:169], v[190:193], v[100:103]
	v_mfma_f32_16x16x32_bf16 v[96:99], v[174:177], v[190:193], v[96:99]
	v_mfma_f32_16x16x32_bf16 v[84:87], v[166:169], v[198:201], v[84:87]
	v_mfma_f32_16x16x32_bf16 v[80:83], v[174:177], v[198:201], v[80:83]
	v_mfma_f32_16x16x32_bf16 v[68:71], v[166:169], v[206:209], v[68:71]
	v_mfma_f32_16x16x32_bf16 v[64:67], v[174:177], v[206:209], v[64:67]
	v_mfma_f32_16x16x32_bf16 v[116:119], v[170:173], v[186:189], v[116:119]
	v_mfma_f32_16x16x32_bf16 v[112:115], v[178:181], v[186:189], v[112:115]
	v_mfma_f32_16x16x32_bf16 v[100:103], v[170:173], v[194:197], v[100:103]
	v_mfma_f32_16x16x32_bf16 v[96:99], v[178:181], v[194:197], v[96:99]
	v_mfma_f32_16x16x32_bf16 v[84:87], v[170:173], v[202:205], v[84:87]
	v_mfma_f32_16x16x32_bf16 v[80:83], v[178:181], v[202:205], v[80:83]
	v_mfma_f32_16x16x32_bf16 v[68:71], v[170:173], v[210:213], v[68:71]
	v_mfma_f32_16x16x32_bf16 v[64:67], v[178:181], v[210:213], v[64:67]
	v_mfma_f32_16x16x32_bf16 v[124:127], v[214:217], v[182:185], v[124:127]
	v_mfma_f32_16x16x32_bf16 v[120:123], v[222:225], v[182:185], v[120:123]
	v_mfma_f32_16x16x32_bf16 v[108:111], v[214:217], v[190:193], v[108:111]
	v_mfma_f32_16x16x32_bf16 v[104:107], v[222:225], v[190:193], v[104:107]
	v_mfma_f32_16x16x32_bf16 v[92:95], v[214:217], v[198:201], v[92:95]
	v_mfma_f32_16x16x32_bf16 v[88:91], v[222:225], v[198:201], v[88:91]
	v_mfma_f32_16x16x32_bf16 v[76:79], v[214:217], v[206:209], v[76:79]
	v_mfma_f32_16x16x32_bf16 v[72:75], v[222:225], v[206:209], v[72:75]
	v_mfma_f32_16x16x32_bf16 v[124:127], v[218:221], v[186:189], v[124:127]
	v_mfma_f32_16x16x32_bf16 v[120:123], v[226:229], v[186:189], v[120:123]
	v_mfma_f32_16x16x32_bf16 v[108:111], v[218:221], v[194:197], v[108:111]
	v_mfma_f32_16x16x32_bf16 v[104:107], v[226:229], v[194:197], v[104:107]
	v_mfma_f32_16x16x32_bf16 v[92:95], v[218:221], v[202:205], v[92:95]
	v_mfma_f32_16x16x32_bf16 v[88:91], v[226:229], v[202:205], v[88:91]
	v_mfma_f32_16x16x32_bf16 v[76:79], v[218:221], v[210:213], v[76:79]
	v_mfma_f32_16x16x32_bf16 v[72:75], v[226:229], v[210:213], v[72:75]
	s_setprio 0
	s_barrier
	ds_read_b128 v[182:185], v158 offset:49152
	ds_read_b128 v[186:189], v158 offset:50176
	ds_read_b128 v[190:193], v158 offset:51200
	ds_read_b128 v[194:197], v158 offset:52224
	ds_read_b128 v[198:201], v158 offset:53248
	ds_read_b128 v[202:205], v158 offset:54272
	ds_read_b128 v[206:209], v158 offset:55296
	ds_read_b128 v[210:213], v158 offset:56320
	v_lshl_add_u64 v[130:131], v[130:131], 0, s[28:29]
	s_mov_b32 m0, s19
	s_nop 0
	global_load_lds_dwordx4 v[130:131], off
	v_lshl_add_u64 v[130:131], v[132:133], 0, s[28:29]
	s_add_i32 m0, s19, 0x2000
	s_nop 0
	global_load_lds_dwordx4 v[130:131], off
	v_lshl_add_u64 v[130:131], v[134:135], 0, s[28:29]
	s_mov_b32 m0, s44
	s_nop 0
	global_load_lds_dwordx4 v[130:131], off
	v_lshl_add_u64 v[130:131], v[136:137], 0, s[28:29]
	s_mov_b32 m0, s45
	s_add_u32 s14, s14, 0x40080
	s_addc_u32 s15, s15, 0
	global_load_lds_dwordx4 v[130:131], off
	s_add_i32 s18, s18, s5
	v_lshl_add_u64 v[130:131], s[14:15], 0, v[128:129]
	s_mov_b32 m0, s18
	s_nop 0
	global_load_lds_dwordx4 v[130:131], off
	v_lshl_add_u64 v[130:131], s[14:15], 0, v[144:145]
	s_add_i32 m0, s18, 0x2000
	s_nop 0
	global_load_lds_dwordx4 v[130:131], off
	s_waitcnt vmcnt(8) lgkmcnt(0)
	s_barrier
	s_setprio 1
	v_mfma_f32_16x16x32_bf16 v[52:55], v[166:169], v[182:185], v[52:55]
	v_mfma_f32_16x16x32_bf16 v[48:51], v[174:177], v[182:185], v[48:51]
	v_mfma_f32_16x16x32_bf16 v[36:39], v[166:169], v[190:193], v[36:39]
	v_mfma_f32_16x16x32_bf16 v[32:35], v[174:177], v[190:193], v[32:35]
	v_mfma_f32_16x16x32_bf16 v[20:23], v[166:169], v[198:201], v[20:23]
	v_mfma_f32_16x16x32_bf16 v[16:19], v[174:177], v[198:201], v[16:19]
	v_mfma_f32_16x16x32_bf16 v[4:7], v[166:169], v[206:209], v[4:7]
	v_mfma_f32_16x16x32_bf16 v[0:3], v[174:177], v[206:209], v[0:3]
	v_mfma_f32_16x16x32_bf16 v[52:55], v[170:173], v[186:189], v[52:55]
	v_mfma_f32_16x16x32_bf16 v[48:51], v[178:181], v[186:189], v[48:51]
	v_mfma_f32_16x16x32_bf16 v[36:39], v[170:173], v[194:197], v[36:39]
	v_mfma_f32_16x16x32_bf16 v[32:35], v[178:181], v[194:197], v[32:35]
	v_mfma_f32_16x16x32_bf16 v[20:23], v[170:173], v[202:205], v[20:23]
	v_mfma_f32_16x16x32_bf16 v[16:19], v[178:181], v[202:205], v[16:19]
	v_mfma_f32_16x16x32_bf16 v[4:7], v[170:173], v[210:213], v[4:7]
	v_mfma_f32_16x16x32_bf16 v[0:3], v[178:181], v[210:213], v[0:3]
	v_mfma_f32_16x16x32_bf16 v[60:63], v[214:217], v[182:185], v[60:63]
	v_mfma_f32_16x16x32_bf16 v[56:59], v[222:225], v[182:185], v[56:59]
	v_mfma_f32_16x16x32_bf16 v[44:47], v[214:217], v[190:193], v[44:47]
	v_mfma_f32_16x16x32_bf16 v[40:43], v[222:225], v[190:193], v[40:43]
	v_mfma_f32_16x16x32_bf16 v[28:31], v[214:217], v[198:201], v[28:31]
	v_mfma_f32_16x16x32_bf16 v[24:27], v[222:225], v[198:201], v[24:27]
	v_mfma_f32_16x16x32_bf16 v[12:15], v[214:217], v[206:209], v[12:15]
	v_mfma_f32_16x16x32_bf16 v[8:11], v[222:225], v[206:209], v[8:11]
	v_mfma_f32_16x16x32_bf16 v[60:63], v[218:221], v[186:189], v[60:63]
	v_mfma_f32_16x16x32_bf16 v[56:59], v[226:229], v[186:189], v[56:59]
	v_mfma_f32_16x16x32_bf16 v[44:47], v[218:221], v[194:197], v[44:47]
	v_mfma_f32_16x16x32_bf16 v[40:43], v[226:229], v[194:197], v[40:43]
	v_mfma_f32_16x16x32_bf16 v[28:31], v[218:221], v[202:205], v[28:31]
	v_mfma_f32_16x16x32_bf16 v[24:27], v[226:229], v[202:205], v[24:27]
	v_mfma_f32_16x16x32_bf16 v[12:15], v[218:221], v[210:213], v[12:15]
	v_mfma_f32_16x16x32_bf16 v[8:11], v[226:229], v[210:213], v[8:11]
	s_setprio 0
	s_add_i32 s92, s92, 2
	s_add_u32 s30, s30, 0x100
	s_addc_u32 s31, s31, 0
	s_add_u32 s25, s25, 0x100
	s_addc_u32 s47, s47, 0
	s_cmp_gt_u32 s92, 13
	s_cbranch_scc1 .Lg1_exit
	s_barrier
	s_branch .LBB0_391

.LBB0_488:
	s_or_b64 exec, exec, s[8:9]
	v_ashrrev_i32_e32 v0, 6, v141
	v_readlane_b32 s0, v255, 7
	s_nop 1
	v_add_u32_e32 v0, s0, v0
	s_mov_b32 s0, 0xc000
	v_cmp_gt_i32_e32 vcc, s0, v0
	s_and_saveexec_b64 s[8:9], vcc
	s_cbranch_execz .LBB0_495
	v_and_b32_e32 v1, 63, v141
	v_readfirstlane_b32 s14, v0
	v_lshlrev_b32_e32 v4, 2, v1
	v_lshlrev_b32_e32 v2, 5, v1
	v_lshlrev_b32_e32 v3, 4, v1
	v_xor_b32_e32 v10, 0x80, v4
	v_xor_b32_e32 v11, 0x40, v4
	v_xor_b32_e32 v12, 0x20, v4
	v_xor_b32_e32 v13, 0x10, v4
	v_xor_b32_e32 v14, 0x8, v4
	v_xor_b32_e32 v15, 0x4, v4
	v_cmp_eq_u32_e64 s[44:45], 0, v1
	v_readlane_b32 s36, v252, 10
	v_readlane_b32 s37, v252, 11
	v_readlane_b32 s38, v252, 12
	v_readlane_b32 s39, v252, 13
	v_readlane_b32 s40, v252, 55
	v_readlane_b32 s41, v252, 56
	v_readlane_b32 s42, v252, 43
	v_readlane_b32 s43, v252, 44
.Ln0_loop:
	s_add_i32 s15, s14, s24
	s_cmp_lt_u32 s15, 0xc000
	s_cselect_b32 s47, s15, s14
	s_add_i32 s15, s15, s24
	s_cmp_lt_u32 s15, 0xc000
	s_cselect_b32 s34, s15, s14
	s_add_i32 s15, s15, s24
	s_cmp_lt_u32 s15, 0xc000
	s_cselect_b32 s35, s15, s14
	s_add_i32 s15, s15, s24
	s_cmp_lt_u32 s14, 0x4000
	s_cselect_b32 s0, s36, s38
	s_cselect_b32 s1, s37, s39
	s_cselect_b32 s12, 0, 0x4000
	s_sub_u32 s12, s14, s12
	s_lshl_b32 s12, s12, 12
	s_add_u32 s0, s0, s12
	s_addc_u32 s1, s1, 0
	global_load_dwordx4 v[32:35], v2, s[0:1]
	global_load_dwordx4 v[36:39], v2, s[0:1] offset:16
	global_load_dwordx4 v[40:43], v2, s[0:1] offset:2048
	global_load_dwordx4 v[44:47], v2, s[0:1] offset:2064
	s_cmp_lt_u32 s47, 0x4000
	s_cselect_b32 s0, s36, s38
	s_cselect_b32 s1, s37, s39
	s_cselect_b32 s12, 0, 0x4000
	s_sub_u32 s12, s47, s12
	s_lshl_b32 s12, s12, 12
	s_add_u32 s0, s0, s12
	s_addc_u32 s1, s1, 0
	global_load_dwordx4 v[48:51], v2, s[0:1]
	global_load_dwordx4 v[52:55], v2, s[0:1] offset:16
	global_load_dwordx4 v[56:59], v2, s[0:1] offset:2048
	global_load_dwordx4 v[60:63], v2, s[0:1] offset:2064
	s_cmp_lt_u32 s34, 0x4000
	s_cselect_b32 s0, s36, s38
	s_cselect_b32 s1, s37, s39
	s_cselect_b32 s12, 0, 0x4000
	s_sub_u32 s12, s34, s12
	s_lshl_b32 s12, s12, 12
	s_add_u32 s0, s0, s12
	s_addc_u32 s1, s1, 0
	global_load_dwordx4 v[64:67], v2, s[0:1]
	global_load_dwordx4 v[68:71], v2, s[0:1] offset:16
	global_load_dwordx4 v[72:75], v2, s[0:1] offset:2048
	global_load_dwordx4 v[76:79], v2, s[0:1] offset:2064
	s_cmp_lt_u32 s35, 0x4000
	s_cselect_b32 s0, s36, s38
	s_cselect_b32 s1, s37, s39
	s_cselect_b32 s12, 0, 0x4000
	s_sub_u32 s12, s35, s12
	s_lshl_b32 s12, s12, 12
	s_add_u32 s0, s0, s12
	s_addc_u32 s1, s1, 0
	global_load_dwordx4 v[80:83], v2, s[0:1]
	global_load_dwordx4 v[84:87], v2, s[0:1] offset:16
	global_load_dwordx4 v[88:91], v2, s[0:1] offset:2048
	global_load_dwordx4 v[92:95], v2, s[0:1] offset:2064
	s_lshl_b32 s12, s14, 11
	s_add_u32 s4, s40, s12
	s_addc_u32 s5, s41, 0
	s_lshl_b32 s12, s47, 11
	s_add_u32 s50, s40, s12
	s_addc_u32 s51, s41, 0
	s_lshl_b32 s12, s34, 11
	s_add_u32 s18, s40, s12
	s_addc_u32 s19, s41, 0
	s_lshl_b32 s12, s35, 11
	s_add_u32 s30, s40, s12
	s_addc_u32 s31, s41, 0
	s_waitcnt vmcnt(0)
	v_pk_mul_f32 v[106:107], v[32:33], v[32:33]
	v_pk_mul_f32 v[108:109], v[34:35], v[34:35]
	v_add_f32_e32 v104, v106, v107
	v_add_f32_e32 v104, v104, v108
	v_pk_mul_f32 v[110:111], v[36:37], v[36:37]
	v_add_f32_e32 v104, v104, v109
	v_add_f32_e32 v104, v104, v110
	v_pk_mul_f32 v[112:113], v[38:39], v[38:39]
	v_add_f32_e32 v104, v104, v111
	v_add_f32_e32 v104, v104, v112
	v_add_f32_e32 v104, v104, v113
	v_pk_mul_f32 v[106:107], v[40:41], v[40:41]
	v_pk_mul_f32 v[108:109], v[42:43], v[42:43]
	v_add_f32_e32 v105, v106, v107
	v_add_f32_e32 v105, v105, v108
	v_pk_mul_f32 v[110:111], v[44:45], v[44:45]
	v_add_f32_e32 v105, v105, v109
	v_add_f32_e32 v105, v105, v110
	v_pk_mul_f32 v[112:113], v[46:47], v[46:47]
	v_add_f32_e32 v105, v105, v111
	v_add_f32_e32 v105, v105, v112
	v_add_f32_e32 v105, v105, v113
	v_add_f32_e32 v96, v104, v105
	v_cvt_pk_bf16_f32 v32, v32, v33
	v_cvt_pk_bf16_f32 v33, v34, v35
	v_cvt_pk_bf16_f32 v34, v36, v37
	v_cvt_pk_bf16_f32 v35, v38, v39
	v_cvt_pk_bf16_f32 v40, v40, v41
	v_cvt_pk_bf16_f32 v41, v42, v43
	v_cvt_pk_bf16_f32 v42, v44, v45
	v_cvt_pk_bf16_f32 v43, v46, v47
	global_store_dwordx4 v3, v[32:35], s[4:5]
	global_store_dwordx4 v3, v[40:43], s[4:5] offset:1024
	v_pk_mul_f32 v[106:107], v[48:49], v[48:49]
	v_pk_mul_f32 v[108:109], v[50:51], v[50:51]
	v_add_f32_e32 v104, v106, v107
	v_add_f32_e32 v104, v104, v108
	v_pk_mul_f32 v[110:111], v[52:53], v[52:53]
	v_add_f32_e32 v104, v104, v109
	v_add_f32_e32 v104, v104, v110
	v_pk_mul_f32 v[112:113], v[54:55], v[54:55]
	v_add_f32_e32 v104, v104, v111
	v_add_f32_e32 v104, v104, v112
	v_add_f32_e32 v104, v104, v113
	v_pk_mul_f32 v[106:107], v[56:57], v[56:57]
	v_pk_mul_f32 v[108:109], v[58:59], v[58:59]
	v_add_f32_e32 v105, v106, v107
	v_add_f32_e32 v105, v105, v108
	v_pk_mul_f32 v[110:111], v[60:61], v[60:61]
	v_add_f32_e32 v105, v105, v109
	v_add_f32_e32 v105, v105, v110
	v_pk_mul_f32 v[112:113], v[62:63], v[62:63]
	v_add_f32_e32 v105, v105, v111
	v_add_f32_e32 v105, v105, v112
	v_add_f32_e32 v105, v105, v113
	v_add_f32_e32 v97, v104, v105
	v_cvt_pk_bf16_f32 v48, v48, v49
	v_cvt_pk_bf16_f32 v49, v50, v51
	v_cvt_pk_bf16_f32 v50, v52, v53
	v_cvt_pk_bf16_f32 v51, v54, v55
	v_cvt_pk_bf16_f32 v56, v56, v57
	v_cvt_pk_bf16_f32 v57, v58, v59
	v_cvt_pk_bf16_f32 v58, v60, v61
	v_cvt_pk_bf16_f32 v59, v62, v63
	global_store_dwordx4 v3, v[48:51], s[50:51]
	global_store_dwordx4 v3, v[56:59], s[50:51] offset:1024
	v_pk_mul_f32 v[106:107], v[64:65], v[64:65]
	v_pk_mul_f32 v[108:109], v[66:67], v[66:67]
	v_add_f32_e32 v104, v106, v107
	v_add_f32_e32 v104, v104, v108
	v_pk_mul_f32 v[110:111], v[68:69], v[68:69]
	v_add_f32_e32 v104, v104, v109
	v_add_f32_e32 v104, v104, v110
	v_pk_mul_f32 v[112:113], v[70:71], v[70:71]
	v_add_f32_e32 v104, v104, v111
	v_add_f32_e32 v104, v104, v112
	v_add_f32_e32 v104, v104, v113
	v_pk_mul_f32 v[106:107], v[72:73], v[72:73]
	v_pk_mul_f32 v[108:109], v[74:75], v[74:75]
	v_add_f32_e32 v105, v106, v107
	v_add_f32_e32 v105, v105, v108
	v_pk_mul_f32 v[110:111], v[76:77], v[76:77]
	v_add_f32_e32 v105, v105, v109
	v_add_f32_e32 v105, v105, v110
	v_pk_mul_f32 v[112:113], v[78:79], v[78:79]
	v_add_f32_e32 v105, v105, v111
	v_add_f32_e32 v105, v105, v112
	v_add_f32_e32 v105, v105, v113
	v_add_f32_e32 v98, v104, v105
	v_cvt_pk_bf16_f32 v64, v64, v65
	v_cvt_pk_bf16_f32 v65, v66, v67
	v_cvt_pk_bf16_f32 v66, v68, v69
	v_cvt_pk_bf16_f32 v67, v70, v71
	v_cvt_pk_bf16_f32 v72, v72, v73
	v_cvt_pk_bf16_f32 v73, v74, v75
	v_cvt_pk_bf16_f32 v74, v76, v77
	v_cvt_pk_bf16_f32 v75, v78, v79
	global_store_dwordx4 v3, v[64:67], s[18:19]
	global_store_dwordx4 v3, v[72:75], s[18:19] offset:1024
	v_pk_mul_f32 v[106:107], v[80:81], v[80:81]
	v_pk_mul_f32 v[108:109], v[82:83], v[82:83]
	v_add_f32_e32 v104, v106, v107
	v_add_f32_e32 v104, v104, v108
	v_pk_mul_f32 v[110:111], v[84:85], v[84:85]
	v_add_f32_e32 v104, v104, v109
	v_add_f32_e32 v104, v104, v110
	v_pk_mul_f32 v[112:113], v[86:87], v[86:87]
	v_add_f32_e32 v104, v104, v111
	v_add_f32_e32 v104, v104, v112
	v_add_f32_e32 v104, v104, v113
	v_pk_mul_f32 v[106:107], v[88:89], v[88:89]
	v_pk_mul_f32 v[108:109], v[90:91], v[90:91]
	v_add_f32_e32 v105, v106, v107
	v_add_f32_e32 v105, v105, v108
	v_pk_mul_f32 v[110:111], v[92:93], v[92:93]
	v_add_f32_e32 v105, v105, v109
	v_add_f32_e32 v105, v105, v110
	v_pk_mul_f32 v[112:113], v[94:95], v[94:95]
	v_add_f32_e32 v105, v105, v111
	v_add_f32_e32 v105, v105, v112
	v_add_f32_e32 v105, v105, v113
	v_add_f32_e32 v99, v104, v105
	v_cvt_pk_bf16_f32 v80, v80, v81
	v_cvt_pk_bf16_f32 v81, v82, v83
	v_cvt_pk_bf16_f32 v82, v84, v85
	v_cvt_pk_bf16_f32 v83, v86, v87
	v_cvt_pk_bf16_f32 v88, v88, v89
	v_cvt_pk_bf16_f32 v89, v90, v91
	v_cvt_pk_bf16_f32 v90, v92, v93
	v_cvt_pk_bf16_f32 v91, v94, v95
	global_store_dwordx4 v3, v[80:83], s[30:31]
	global_store_dwordx4 v3, v[88:91], s[30:31] offset:1024
	ds_bpermute_b32 v100, v10, v96
	ds_bpermute_b32 v101, v10, v97
	ds_bpermute_b32 v102, v10, v98
	ds_bpermute_b32 v103, v10, v99
	s_waitcnt lgkmcnt(0)
	v_add_f32_e32 v96, v96, v100
	v_add_f32_e32 v97, v97, v101
	v_add_f32_e32 v98, v98, v102
	v_add_f32_e32 v99, v99, v103
	ds_bpermute_b32 v100, v11, v96
	ds_bpermute_b32 v101, v11, v97
	ds_bpermute_b32 v102, v11, v98
	ds_bpermute_b32 v103, v11, v99
	s_waitcnt lgkmcnt(0)
	v_add_f32_e32 v96, v96, v100
	v_add_f32_e32 v97, v97, v101
	v_add_f32_e32 v98, v98, v102
	v_add_f32_e32 v99, v99, v103
	ds_bpermute_b32 v100, v12, v96
	ds_bpermute_b32 v101, v12, v97
	ds_bpermute_b32 v102, v12, v98
	ds_bpermute_b32 v103, v12, v99
	s_waitcnt lgkmcnt(0)
	v_add_f32_e32 v96, v96, v100
	v_add_f32_e32 v97, v97, v101
	v_add_f32_e32 v98, v98, v102
	v_add_f32_e32 v99, v99, v103
	ds_bpermute_b32 v100, v13, v96
	ds_bpermute_b32 v101, v13, v97
	ds_bpermute_b32 v102, v13, v98
	ds_bpermute_b32 v103, v13, v99
	s_waitcnt lgkmcnt(0)
	v_add_f32_e32 v96, v96, v100
	v_add_f32_e32 v97, v97, v101
	v_add_f32_e32 v98, v98, v102
	v_add_f32_e32 v99, v99, v103
	ds_bpermute_b32 v100, v14, v96
	ds_bpermute_b32 v101, v14, v97
	ds_bpermute_b32 v102, v14, v98
	ds_bpermute_b32 v103, v14, v99
	s_waitcnt lgkmcnt(0)
	v_add_f32_e32 v96, v96, v100
	v_add_f32_e32 v97, v97, v101
	v_add_f32_e32 v98, v98, v102
	v_add_f32_e32 v99, v99, v103
	ds_bpermute_b32 v100, v15, v96
	ds_bpermute_b32 v101, v15, v97
	ds_bpermute_b32 v102, v15, v98
	ds_bpermute_b32 v103, v15, v99
	s_waitcnt lgkmcnt(0)
	v_add_f32_e32 v96, v96, v100
	v_add_f32_e32 v97, v97, v101
	v_add_f32_e32 v98, v98, v102
	v_add_f32_e32 v99, v99, v103
	s_mov_b64 s[48:49], exec
	s_and_b64 exec, exec, s[44:45]
	s_lshl_b32 s12, s14, 2
	s_add_u32 s0, s42, s12
	s_addc_u32 s1, s43, 0
	global_store_dword v129, v96, s[0:1]
	s_lshl_b32 s12, s47, 2
	s_add_u32 s0, s42, s12
	s_addc_u32 s1, s43, 0
	global_store_dword v129, v97, s[0:1]
	s_lshl_b32 s12, s34, 2
	s_add_u32 s0, s42, s12
	s_addc_u32 s1, s43, 0
	global_store_dword v129, v98, s[0:1]
	s_lshl_b32 s12, s35, 2
	s_add_u32 s0, s42, s12
	s_addc_u32 s1, s43, 0
	global_store_dword v129, v99, s[0:1]
	s_mov_b64 exec, s[48:49]
	s_mov_b32 s14, s15
	s_cmp_lt_u32 s14, 0xc000
	s_cbranch_scc1 .Ln0_loop
	v_readlane_b32 s36, v252, 10
	v_readlane_b32 s37, v252, 11
	v_readlane_b32 s38, v252, 12
	v_readlane_b32 s39, v252, 13
	v_readlane_b32 s40, v252, 14
	v_readlane_b32 s41, v252, 15
	v_readlane_b32 s42, v252, 16
	v_readlane_b32 s43, v252, 17
	v_readlane_b32 s44, v252, 18
	v_readlane_b32 s45, v252, 19
	v_readlane_b32 s46, v252, 20
	v_readlane_b32 s47, v252, 21
	v_readlane_b32 s48, v252, 22
	v_readlane_b32 s49, v252, 23
	v_readlane_b32 s50, v252, 24
	v_readlane_b32 s51, v252, 25
